# SSD + prompt-attention MFMA operand reads issued ahead with counted waits (rotating operand quads)
# baseline (speedup 1.0000x reference)
.LBB0_1523:
	s_or_b64 exec, exec, s[14:15]
	global_load_dwordx4 v[8:11], v[162:163], off
	s_cmp_gt_i32 s24, s23
	s_cbranch_scc1 .LBB0_1527
	s_and_b32 s14, s25, 1
	s_mul_i32 s15, s14, 0x3400
	v_add3_u32 v3, v127, s15, v171
	ds_read_b128 v[180:183], v3
	ds_read_b128 v[188:191], v3 offset:6656
	ds_read_b128 v[196:199], v3 offset:32
	ds_read_b128 v[204:207], v3 offset:6688
	s_add_i32 s15, s24, 63
	s_cmp_le_i32 s15, s21
	s_waitcnt vmcnt(7) lgkmcnt(3)
	v_mfma_f32_32x32x16_bf16 v[66:81], v[180:183], v[114:117], 0
	ds_read_b128 v[212:215], v3 offset:64
	s_waitcnt lgkmcnt(3)
	v_mfma_f32_32x32x16_bf16 v[50:65], v[188:191], v[114:117], 0
	ds_read_b128 v[180:183], v3 offset:6720
	s_waitcnt vmcnt(6) lgkmcnt(3)
	v_mfma_f32_32x32x16_bf16 v[66:81], v[196:199], v[110:113], v[66:81]
	ds_read_b128 v[188:191], v3 offset:96
	s_waitcnt lgkmcnt(3)
	v_mfma_f32_32x32x16_bf16 v[50:65], v[204:207], v[110:113], v[50:65]
	ds_read_b128 v[196:199], v3 offset:6752
	s_waitcnt vmcnt(5) lgkmcnt(3)
	v_mfma_f32_32x32x16_bf16 v[66:81], v[212:215], v[106:109], v[66:81]
	ds_read_b128 v[204:207], v3 offset:128
	s_waitcnt lgkmcnt(3)
	v_mfma_f32_32x32x16_bf16 v[50:65], v[180:183], v[106:109], v[50:65]
	ds_read_b128 v[212:215], v3 offset:6784
	s_waitcnt vmcnt(4) lgkmcnt(3)
	v_mfma_f32_32x32x16_bf16 v[66:81], v[188:191], v[102:105], v[66:81]
	ds_read_b128 v[180:183], v3 offset:160
	s_waitcnt lgkmcnt(3)
	v_mfma_f32_32x32x16_bf16 v[50:65], v[196:199], v[102:105], v[50:65]
	ds_read_b128 v[188:191], v3 offset:6816
	s_waitcnt vmcnt(3) lgkmcnt(3)
	v_mfma_f32_32x32x16_bf16 v[66:81], v[204:207], v[98:101], v[66:81]
	s_waitcnt lgkmcnt(2)
	v_mfma_f32_32x32x16_bf16 v[50:65], v[212:215], v[98:101], v[50:65]
	s_waitcnt vmcnt(2) lgkmcnt(1)
	v_mfma_f32_32x32x16_bf16 v[66:81], v[180:183], v[94:97], v[66:81]
	s_waitcnt lgkmcnt(0)
	v_mfma_f32_32x32x16_bf16 v[50:65], v[188:191], v[94:97], v[50:65]
	s_cbranch_scc1 .LBB0_1526
	v_add_u32_e32 v3, s24, v168
	v_cmp_gt_i32_e32 vcc, v3, v156
	s_nop 5
	v_cndmask_b32_e32 v12, v66, v173, vcc
	v_cmp_lt_i32_e32 vcc, v3, v156
	s_nop 1
	v_cndmask_b32_e32 v66, v12, v66, vcc
	v_add_u32_e32 v12, 2, v3
	v_cndmask_b32_e32 v67, v173, v67, vcc
	v_cmp_le_i32_e32 vcc, v12, v156
	v_add_u32_e32 v12, 3, v3
	s_nop 0
	v_cndmask_b32_e32 v68, v173, v68, vcc
	v_cmp_le_i32_e32 vcc, v12, v156
	v_add_u32_e32 v12, 8, v3
	s_nop 0
	v_cndmask_b32_e32 v69, v173, v69, vcc
	v_cmp_le_i32_e32 vcc, v12, v156
	v_add_u32_e32 v12, 9, v3
	s_nop 0
	v_cndmask_b32_e32 v70, v173, v70, vcc
	v_cmp_le_i32_e32 vcc, v12, v156
	v_add_u32_e32 v12, 10, v3
	s_nop 0
	v_cndmask_b32_e32 v71, v173, v71, vcc
	v_cmp_le_i32_e32 vcc, v12, v156
	v_add_u32_e32 v12, 11, v3
	s_nop 0
	v_cndmask_b32_e32 v72, v173, v72, vcc
	v_cmp_le_i32_e32 vcc, v12, v156
	v_add_u32_e32 v12, 16, v3
	s_nop 0
	v_cndmask_b32_e32 v73, v173, v73, vcc
	v_cmp_le_i32_e32 vcc, v12, v156
	v_add_u32_e32 v12, 17, v3
	s_nop 0
	v_cndmask_b32_e32 v74, v173, v74, vcc
	v_cmp_le_i32_e32 vcc, v12, v156
	v_add_u32_e32 v12, 18, v3
	s_nop 0
	v_cndmask_b32_e32 v75, v173, v75, vcc
	v_cmp_le_i32_e32 vcc, v12, v156
	v_add_u32_e32 v12, 19, v3
	s_nop 0
	v_cndmask_b32_e32 v76, v173, v76, vcc
	v_cmp_le_i32_e32 vcc, v12, v156
	v_add_u32_e32 v12, 24, v3
	s_nop 0
	v_cndmask_b32_e32 v77, v173, v77, vcc
	v_cmp_le_i32_e32 vcc, v12, v156
	v_add_u32_e32 v12, 25, v3
	s_nop 0
	v_cndmask_b32_e32 v78, v173, v78, vcc
	v_cmp_le_i32_e32 vcc, v12, v156
	v_add_u32_e32 v12, 26, v3
	s_nop 0
	v_cndmask_b32_e32 v79, v173, v79, vcc
	v_cmp_le_i32_e32 vcc, v12, v156
	v_add_u32_e32 v12, 27, v3
	s_nop 0
	v_cndmask_b32_e32 v80, v173, v80, vcc
	v_cmp_le_i32_e32 vcc, v12, v156
	v_add_u32_e32 v12, 32, v3
	s_nop 0
	v_cndmask_b32_e32 v81, v173, v81, vcc
	v_cmp_le_i32_e32 vcc, v12, v156
	v_add_u32_e32 v12, 33, v3
	s_nop 0
	v_cndmask_b32_e32 v50, v173, v50, vcc
	v_cmp_le_i32_e32 vcc, v12, v156
	v_add_u32_e32 v12, 34, v3
	s_nop 0
	v_cndmask_b32_e32 v51, v173, v51, vcc
	v_cmp_le_i32_e32 vcc, v12, v156
	v_add_u32_e32 v12, 35, v3
	s_nop 0
	v_cndmask_b32_e32 v52, v173, v52, vcc
	v_cmp_le_i32_e32 vcc, v12, v156
	v_add_u32_e32 v12, 40, v3
	s_nop 0
	v_cndmask_b32_e32 v53, v173, v53, vcc
	v_cmp_le_i32_e32 vcc, v12, v156
	v_add_u32_e32 v12, 41, v3
	s_nop 0
	v_cndmask_b32_e32 v54, v173, v54, vcc
	v_cmp_le_i32_e32 vcc, v12, v156
	v_add_u32_e32 v12, 42, v3
	s_nop 0
	v_cndmask_b32_e32 v55, v173, v55, vcc
	v_cmp_le_i32_e32 vcc, v12, v156
	v_add_u32_e32 v12, 43, v3
	s_nop 0
	v_cndmask_b32_e32 v56, v173, v56, vcc
	v_cmp_le_i32_e32 vcc, v12, v156
	v_add_u32_e32 v12, 48, v3
	s_nop 0
	v_cndmask_b32_e32 v57, v173, v57, vcc
	v_cmp_le_i32_e32 vcc, v12, v156
	v_add_u32_e32 v12, 49, v3
	s_nop 0
	v_cndmask_b32_e32 v58, v173, v58, vcc
	v_cmp_le_i32_e32 vcc, v12, v156
	v_add_u32_e32 v12, 50, v3
	s_nop 0
	v_cndmask_b32_e32 v59, v173, v59, vcc
	v_cmp_le_i32_e32 vcc, v12, v156
	v_add_u32_e32 v12, 51, v3
	s_nop 0
	v_cndmask_b32_e32 v60, v173, v60, vcc
	v_cmp_le_i32_e32 vcc, v12, v156
	v_add_u32_e32 v12, 56, v3
	s_nop 0
	v_cndmask_b32_e32 v61, v173, v61, vcc
	v_cmp_le_i32_e32 vcc, v12, v156
	v_add_u32_e32 v12, 57, v3
	s_nop 0
	v_cndmask_b32_e32 v62, v173, v62, vcc
	v_cmp_le_i32_e32 vcc, v12, v156
	v_add_u32_e32 v12, 58, v3
	v_add_u32_e32 v3, 59, v3
	v_cndmask_b32_e32 v63, v173, v63, vcc
	v_cmp_le_i32_e32 vcc, v12, v156
	s_nop 1
	v_cndmask_b32_e32 v64, v173, v64, vcc
	v_cmp_le_i32_e32 vcc, v3, v156
	s_nop 1
	v_cndmask_b32_e32 v65, v173, v65, vcc
.LBB0_1526:
	s_nop 7
	v_max3_f32 v3, v66, s17, v67
	v_max3_f32 v3, v3, v68, v69
	v_max3_f32 v3, v3, v70, v71
	v_max3_f32 v3, v3, v72, v73
	v_max3_f32 v3, v3, v74, v75
	v_max3_f32 v3, v3, v76, v77
	v_max3_f32 v3, v3, v78, v79
	v_max3_f32 v3, v3, v80, v81
	v_max3_f32 v3, v3, v50, v51
	v_max3_f32 v3, v3, v52, v53
	v_max3_f32 v3, v3, v54, v55
	v_max3_f32 v3, v3, v56, v57
	v_and_b32_e32 v13, 64, v174
	v_max3_f32 v3, v3, v58, v59
	v_xor_b32_e32 v12, 32, v174
	v_add_u32_e32 v13, 64, v13
	v_max3_f32 v3, v3, v60, v61
	v_cmp_lt_i32_e32 vcc, v12, v13
	v_max3_f32 v3, v3, v62, v63
	v_max3_f32 v3, v3, v64, v65
	v_cndmask_b32_e32 v12, v174, v12, vcc
	v_lshlrev_b32_e32 v12, 2, v12
	ds_bpermute_b32 v12, v12, v3
	s_mulk_i32 s14, 0x2200
	s_waitcnt lgkmcnt(0)
	v_max3_f32 v3, v175, v3, v12
	v_sub_f32_e32 v13, v66, v3
	v_exp_f32_e32 v13, v13
	v_sub_f32_e32 v15, v67, v3
	v_exp_f32_e32 v15, v15
	v_sub_f32_e32 v16, v68, v3
	v_exp_f32_e32 v16, v16
	v_sub_f32_e32 v17, v69, v3
	v_exp_f32_e32 v17, v17
	v_sub_f32_e32 v66, v70, v3
	v_add_f32_e32 v14, 0, v13
	v_exp_f32_e32 v66, v66
	v_sub_f32_e32 v67, v71, v3
	v_add_f32_e32 v14, v15, v14
	v_exp_f32_e32 v67, v67
	v_sub_f32_e32 v68, v72, v3
	v_add_f32_e32 v14, v16, v14
	v_exp_f32_e32 v68, v68
	v_sub_f32_e32 v69, v73, v3
	v_add_f32_e32 v14, v17, v14
	v_exp_f32_e32 v69, v69
	v_sub_f32_e32 v70, v74, v3
	v_add_f32_e32 v14, v66, v14
	v_exp_f32_e32 v70, v70
	v_sub_f32_e32 v71, v75, v3
	v_add_f32_e32 v14, v67, v14
	v_exp_f32_e32 v71, v71
	v_sub_f32_e32 v72, v76, v3
	v_add_f32_e32 v14, v68, v14
	v_exp_f32_e32 v72, v72
	v_sub_f32_e32 v73, v77, v3
	v_add_f32_e32 v14, v69, v14
	v_exp_f32_e32 v73, v73
	v_sub_f32_e32 v74, v78, v3
	v_add_f32_e32 v14, v70, v14
	v_exp_f32_e32 v74, v74
	v_sub_f32_e32 v75, v79, v3
	v_add_f32_e32 v14, v71, v14
	v_exp_f32_e32 v75, v75
	v_sub_f32_e32 v76, v80, v3
	v_add_f32_e32 v14, v72, v14
	v_exp_f32_e32 v76, v76
	v_sub_f32_e32 v77, v81, v3
	v_add_f32_e32 v14, v73, v14
	v_exp_f32_e32 v77, v77
	v_sub_f32_e32 v50, v50, v3
	v_add_f32_e32 v14, v74, v14
	v_exp_f32_e32 v78, v50
	v_sub_f32_e32 v50, v51, v3
	v_add_f32_e32 v14, v75, v14
	v_exp_f32_e32 v79, v50
	v_sub_f32_e32 v50, v52, v3
	v_add_f32_e32 v14, v76, v14
	v_exp_f32_e32 v80, v50
	v_sub_f32_e32 v50, v53, v3
	v_add_f32_e32 v14, v77, v14
	v_exp_f32_e32 v81, v50
	v_sub_f32_e32 v50, v54, v3
	v_exp_f32_e32 v54, v50
	v_sub_f32_e32 v50, v55, v3
	v_add_f32_e32 v14, v78, v14
	v_exp_f32_e32 v55, v50
	v_sub_f32_e32 v50, v56, v3
	v_add_f32_e32 v14, v79, v14
	v_exp_f32_e32 v56, v50
	v_sub_f32_e32 v50, v57, v3
	v_add_f32_e32 v14, v80, v14
	v_exp_f32_e32 v57, v50
	v_sub_f32_e32 v50, v58, v3
	v_add_f32_e32 v14, v81, v14
	v_exp_f32_e32 v58, v50
	v_sub_f32_e32 v50, v59, v3
	v_add_f32_e32 v14, v54, v14
	v_exp_f32_e32 v59, v50
	v_sub_f32_e32 v50, v60, v3
	v_add_f32_e32 v14, v55, v14
	v_exp_f32_e32 v60, v50
	v_sub_f32_e32 v50, v61, v3
	v_add_f32_e32 v14, v56, v14
	v_exp_f32_e32 v61, v50
	v_sub_f32_e32 v50, v62, v3
	v_add_f32_e32 v14, v57, v14
	v_exp_f32_e32 v62, v50
	v_sub_f32_e32 v50, v63, v3
	v_add_f32_e32 v14, v58, v14
	v_exp_f32_e32 v63, v50
	v_sub_f32_e32 v50, v64, v3
	v_add_f32_e32 v14, v59, v14
	v_sub_f32_e32 v12, v175, v3
	v_exp_f32_e32 v64, v50
	v_sub_f32_e32 v50, v65, v3
	v_add_f32_e32 v14, v60, v14
	v_exp_f32_e32 v65, v50
	v_exp_f32_e32 v12, v12
	v_add_f32_e32 v14, v61, v14
	v_add_f32_e32 v14, v62, v14
	v_add_f32_e32 v14, v63, v14
	v_add_f32_e32 v14, v64, v14
	v_pk_mul_f32 v[48:49], v[48:49], v[12:13] op_sel_hi:[1,0]
	v_pk_mul_f32 v[46:47], v[46:47], v[12:13] op_sel_hi:[1,0]
	v_pk_mul_f32 v[44:45], v[44:45], v[12:13] op_sel_hi:[1,0]
	v_pk_mul_f32 v[42:43], v[42:43], v[12:13] op_sel_hi:[1,0]
	v_pk_mul_f32 v[40:41], v[40:41], v[12:13] op_sel_hi:[1,0]
	v_pk_mul_f32 v[38:39], v[38:39], v[12:13] op_sel_hi:[1,0]
	v_pk_mul_f32 v[36:37], v[36:37], v[12:13] op_sel_hi:[1,0]
	v_pk_mul_f32 v[34:35], v[34:35], v[12:13] op_sel_hi:[1,0]
	v_pk_mul_f32 v[32:33], v[32:33], v[12:13] op_sel_hi:[1,0]
	v_pk_mul_f32 v[30:31], v[30:31], v[12:13] op_sel_hi:[1,0]
	v_pk_mul_f32 v[28:29], v[28:29], v[12:13] op_sel_hi:[1,0]
	v_pk_mul_f32 v[26:27], v[26:27], v[12:13] op_sel_hi:[1,0]
	v_pk_mul_f32 v[24:25], v[24:25], v[12:13] op_sel_hi:[1,0]
	v_pk_mul_f32 v[22:23], v[22:23], v[12:13] op_sel_hi:[1,0]
	v_pk_mul_f32 v[20:21], v[20:21], v[12:13] op_sel_hi:[1,0]
	v_pk_mul_f32 v[18:19], v[18:19], v[12:13] op_sel_hi:[1,0]
	v_add_f32_e32 v176, v65, v14
	v_cvt_pk_bf16_f32 v14, v13, v15
	v_add3_u32 v13, v169, s14, v172
	v_cvt_pk_bf16_f32 v15, v16, v17
	v_cvt_pk_bf16_f32 v16, v66, v67
	v_add_u32_e32 v66, 0x6800, v13
	v_cvt_pk_bf16_f32 v17, v68, v69
	ds_read2_b64 v[180:183], v66 offset1:2
	v_add_u32_e32 v13, 0x7800, v13
	ds_read2_b64 v[188:191], v13 offset0:32 offset1:34
	ds_read2_b64 v[196:199], v66 offset0:4 offset1:6
	ds_read2_b64 v[204:207], v13 offset0:36 offset1:38
	s_waitcnt lgkmcnt(3)
	v_mfma_f32_32x32x16_bf16 v[34:49], v[180:183], v[14:17], v[34:49]
	ds_read2_b64 v[212:215], v66 offset0:8 offset1:10
	v_fmac_f32_e32 v176, v157, v12
	v_mov_b32_e32 v175, v3
	v_mov_b32_e32 v157, v176
	s_waitcnt lgkmcnt(3)
	v_mfma_f32_32x32x16_bf16 v[18:33], v[188:191], v[14:17], v[18:33]
	ds_read2_b64 v[180:183], v13 offset0:40 offset1:42
	v_cvt_pk_bf16_f32 v14, v70, v71
	v_cvt_pk_bf16_f32 v15, v72, v73
	v_cvt_pk_bf16_f32 v16, v74, v75
	v_cvt_pk_bf16_f32 v17, v76, v77
	s_waitcnt lgkmcnt(3)
	s_nop 0
	v_mfma_f32_32x32x16_bf16 v[34:49], v[196:199], v[14:17], v[34:49]
	ds_read2_b64 v[188:191], v66 offset0:12 offset1:14
	s_waitcnt lgkmcnt(3)
	v_mfma_f32_32x32x16_bf16 v[18:33], v[204:207], v[14:17], v[18:33]
	ds_read2_b64 v[196:199], v13 offset0:44 offset1:46
	v_cvt_pk_bf16_f32 v14, v78, v79
	v_cvt_pk_bf16_f32 v15, v80, v81
	v_cvt_pk_bf16_f32 v16, v54, v55
	v_cvt_pk_bf16_f32 v17, v56, v57
	s_waitcnt lgkmcnt(3)
	s_nop 0
	v_mfma_f32_32x32x16_bf16 v[34:49], v[212:215], v[14:17], v[34:49]
	s_waitcnt lgkmcnt(2)
	v_mfma_f32_32x32x16_bf16 v[18:33], v[180:183], v[14:17], v[18:33]
	v_cvt_pk_bf16_f32 v14, v58, v59
	v_cvt_pk_bf16_f32 v15, v60, v61
	v_cvt_pk_bf16_f32 v16, v62, v63
	v_cvt_pk_bf16_f32 v17, v64, v65
	s_waitcnt lgkmcnt(1)
	s_nop 0
	v_mfma_f32_32x32x16_bf16 v[34:49], v[188:191], v[14:17], v[34:49]
	s_waitcnt lgkmcnt(0)
	v_mfma_f32_32x32x16_bf16 v[18:33], v[196:199], v[14:17], v[18:33]

.LBB0_1529:
	s_cmp_le_i32 s22, s23
	s_mov_b64 s[14:15], -1
	s_cbranch_scc0 .LBB0_1533
	v_add_u32_e32 v3, v127, v171
	ds_read_b128 v[180:183], v3 offset:13312
	ds_read_b128 v[188:191], v3 offset:19968
	ds_read_b128 v[196:199], v3 offset:13344
	ds_read_b128 v[204:207], v3 offset:20000
	s_or_b32 s14, s22, 63
	s_cmp_le_i32 s14, s21
	s_waitcnt lgkmcnt(3)
	v_mfma_f32_32x32x16_bf16 v[66:81], v[180:183], v[114:117], 0
	ds_read_b128 v[212:215], v3 offset:13376
	s_waitcnt lgkmcnt(3)
	v_mfma_f32_32x32x16_bf16 v[50:65], v[188:191], v[114:117], 0
	ds_read_b128 v[180:183], v3 offset:20032
	s_waitcnt lgkmcnt(3)
	v_mfma_f32_32x32x16_bf16 v[66:81], v[196:199], v[110:113], v[66:81]
	ds_read_b128 v[188:191], v3 offset:13408
	s_waitcnt lgkmcnt(3)
	v_mfma_f32_32x32x16_bf16 v[50:65], v[204:207], v[110:113], v[50:65]
	ds_read_b128 v[196:199], v3 offset:20064
	s_waitcnt lgkmcnt(3)
	v_mfma_f32_32x32x16_bf16 v[66:81], v[212:215], v[106:109], v[66:81]
	ds_read_b128 v[204:207], v3 offset:13440
	s_waitcnt lgkmcnt(3)
	v_mfma_f32_32x32x16_bf16 v[50:65], v[180:183], v[106:109], v[50:65]
	ds_read_b128 v[212:215], v3 offset:20096
	s_waitcnt lgkmcnt(3)
	v_mfma_f32_32x32x16_bf16 v[66:81], v[188:191], v[102:105], v[66:81]
	ds_read_b128 v[180:183], v3 offset:13472
	s_waitcnt lgkmcnt(3)
	v_mfma_f32_32x32x16_bf16 v[50:65], v[196:199], v[102:105], v[50:65]
	ds_read_b128 v[188:191], v3 offset:20128
	s_waitcnt lgkmcnt(3)
	v_mfma_f32_32x32x16_bf16 v[66:81], v[204:207], v[98:101], v[66:81]
	s_waitcnt lgkmcnt(2)
	v_mfma_f32_32x32x16_bf16 v[50:65], v[212:215], v[98:101], v[50:65]
	s_waitcnt lgkmcnt(1)
	v_mfma_f32_32x32x16_bf16 v[66:81], v[180:183], v[94:97], v[66:81]
	s_waitcnt lgkmcnt(0)
	v_mfma_f32_32x32x16_bf16 v[50:65], v[188:191], v[94:97], v[50:65]
	s_cbranch_scc1 .LBB0_1532
	v_or_b32_e32 v3, s22, v168
	v_cmp_gt_i32_e32 vcc, v3, v156
	s_nop 5
	v_cndmask_b32_e32 v4, v66, v173, vcc
	v_cmp_lt_i32_e32 vcc, v3, v156
	s_nop 1
	v_cndmask_b32_e32 v66, v4, v66, vcc
	v_or_b32_e32 v4, 2, v3
	v_cndmask_b32_e32 v67, v173, v67, vcc
	v_cmp_le_i32_e32 vcc, v4, v156
	v_or_b32_e32 v4, 3, v3
	s_nop 0
	v_cndmask_b32_e32 v68, v173, v68, vcc
	v_cmp_le_i32_e32 vcc, v4, v156
	v_or_b32_e32 v4, 8, v3
	s_nop 0
	v_cndmask_b32_e32 v69, v173, v69, vcc
	v_cmp_le_i32_e32 vcc, v4, v156
	v_or_b32_e32 v4, 9, v3
	s_nop 0
	v_cndmask_b32_e32 v70, v173, v70, vcc
	v_cmp_le_i32_e32 vcc, v4, v156
	v_or_b32_e32 v4, 10, v3
	s_nop 0
	v_cndmask_b32_e32 v71, v173, v71, vcc
	v_cmp_le_i32_e32 vcc, v4, v156
	v_or_b32_e32 v4, 11, v3
	s_nop 0
	v_cndmask_b32_e32 v72, v173, v72, vcc
	v_cmp_le_i32_e32 vcc, v4, v156
	v_or_b32_e32 v4, 16, v3
	s_nop 0
	v_cndmask_b32_e32 v73, v173, v73, vcc
	v_cmp_le_i32_e32 vcc, v4, v156
	v_or_b32_e32 v4, 17, v3
	s_nop 0
	v_cndmask_b32_e32 v74, v173, v74, vcc
	v_cmp_le_i32_e32 vcc, v4, v156
	v_or_b32_e32 v4, 18, v3
	s_nop 0
	v_cndmask_b32_e32 v75, v173, v75, vcc
	v_cmp_le_i32_e32 vcc, v4, v156
	v_or_b32_e32 v4, 19, v3
	s_nop 0
	v_cndmask_b32_e32 v76, v173, v76, vcc
	v_cmp_le_i32_e32 vcc, v4, v156
	v_or_b32_e32 v4, 24, v3
	s_nop 0
	v_cndmask_b32_e32 v77, v173, v77, vcc
	v_cmp_le_i32_e32 vcc, v4, v156
	v_or_b32_e32 v4, 25, v3
	s_nop 0
	v_cndmask_b32_e32 v78, v173, v78, vcc
	v_cmp_le_i32_e32 vcc, v4, v156
	v_or_b32_e32 v4, 26, v3
	s_nop 0
	v_cndmask_b32_e32 v79, v173, v79, vcc
	v_cmp_le_i32_e32 vcc, v4, v156
	v_or_b32_e32 v4, 27, v3
	s_nop 0
	v_cndmask_b32_e32 v80, v173, v80, vcc
	v_cmp_le_i32_e32 vcc, v4, v156
	v_or_b32_e32 v4, 32, v3
	s_nop 0
	v_cndmask_b32_e32 v81, v173, v81, vcc
	v_cmp_le_i32_e32 vcc, v4, v156
	v_or_b32_e32 v4, 33, v3
	s_nop 0
	v_cndmask_b32_e32 v50, v173, v50, vcc
	v_cmp_le_i32_e32 vcc, v4, v156
	v_or_b32_e32 v4, 34, v3
	s_nop 0
	v_cndmask_b32_e32 v51, v173, v51, vcc
	v_cmp_le_i32_e32 vcc, v4, v156
	v_or_b32_e32 v4, 35, v3
	s_nop 0
	v_cndmask_b32_e32 v52, v173, v52, vcc
	v_cmp_le_i32_e32 vcc, v4, v156
	v_or_b32_e32 v4, 40, v3
	s_nop 0
	v_cndmask_b32_e32 v53, v173, v53, vcc
	v_cmp_le_i32_e32 vcc, v4, v156
	v_or_b32_e32 v4, 41, v3
	s_nop 0
	v_cndmask_b32_e32 v54, v173, v54, vcc
	v_cmp_le_i32_e32 vcc, v4, v156
	v_or_b32_e32 v4, 42, v3
	s_nop 0
	v_cndmask_b32_e32 v55, v173, v55, vcc
	v_cmp_le_i32_e32 vcc, v4, v156
	v_or_b32_e32 v4, 43, v3
	s_nop 0
	v_cndmask_b32_e32 v56, v173, v56, vcc
	v_cmp_le_i32_e32 vcc, v4, v156
	v_or_b32_e32 v4, 48, v3
	s_nop 0
	v_cndmask_b32_e32 v57, v173, v57, vcc
	v_cmp_le_i32_e32 vcc, v4, v156
	v_or_b32_e32 v4, 49, v3
	s_nop 0
	v_cndmask_b32_e32 v58, v173, v58, vcc
	v_cmp_le_i32_e32 vcc, v4, v156
	v_or_b32_e32 v4, 50, v3
	s_nop 0
	v_cndmask_b32_e32 v59, v173, v59, vcc
	v_cmp_le_i32_e32 vcc, v4, v156
	v_or_b32_e32 v4, 51, v3
	s_nop 0
	v_cndmask_b32_e32 v60, v173, v60, vcc
	v_cmp_le_i32_e32 vcc, v4, v156
	v_or_b32_e32 v4, 56, v3
	s_nop 0
	v_cndmask_b32_e32 v61, v173, v61, vcc
	v_cmp_le_i32_e32 vcc, v4, v156
	v_or_b32_e32 v4, 57, v3
	s_nop 0
	v_cndmask_b32_e32 v62, v173, v62, vcc
	v_cmp_le_i32_e32 vcc, v4, v156
	v_or_b32_e32 v4, 58, v3
	v_or_b32_e32 v3, 59, v3
	v_cndmask_b32_e32 v63, v173, v63, vcc
	v_cmp_le_i32_e32 vcc, v4, v156
	s_nop 1
	v_cndmask_b32_e32 v64, v173, v64, vcc
	v_cmp_le_i32_e32 vcc, v3, v156
	s_nop 1
	v_cndmask_b32_e32 v65, v173, v65, vcc
.LBB0_1532:
	s_nop 7
	v_max3_f32 v3, v66, s17, v67
	v_max3_f32 v3, v3, v68, v69
	v_max3_f32 v3, v3, v70, v71
	v_max3_f32 v3, v3, v72, v73
	v_max3_f32 v3, v3, v74, v75
	v_max3_f32 v3, v3, v76, v77
	v_max3_f32 v3, v3, v78, v79
	v_max3_f32 v3, v3, v80, v81
	v_max3_f32 v3, v3, v50, v51
	v_max3_f32 v3, v3, v52, v53
	v_max3_f32 v3, v3, v54, v55
	v_max3_f32 v3, v3, v56, v57
	v_max3_f32 v3, v3, v58, v59
	v_max3_f32 v3, v3, v60, v61
	v_mbcnt_hi_u32_b32 v5, -1, v1
	v_max3_f32 v3, v3, v62, v63
	v_and_b32_e32 v6, 64, v5
	v_max3_f32 v4, v3, v64, v65
	v_xor_b32_e32 v3, 32, v5
	v_add_u32_e32 v6, 64, v6
	v_cmp_lt_i32_e32 vcc, v3, v6
	s_mov_b64 s[14:15], 0
	s_nop 0
	v_cndmask_b32_e32 v7, v5, v3, vcc
	v_lshlrev_b32_e32 v7, 2, v7
	ds_bpermute_b32 v7, v7, v4
	s_waitcnt lgkmcnt(0)
	v_max3_f32 v4, v175, v4, v7
	v_sub_f32_e32 v8, v66, v4
	v_exp_f32_e32 v8, v8
	v_sub_f32_e32 v10, v67, v4
	v_exp_f32_e32 v10, v10
	v_sub_f32_e32 v11, v68, v4
	v_exp_f32_e32 v11, v11
	v_sub_f32_e32 v12, v69, v4
	v_exp_f32_e32 v12, v12
	v_sub_f32_e32 v13, v70, v4
	v_add_f32_e32 v9, 0, v8
	v_exp_f32_e32 v13, v13
	v_sub_f32_e32 v14, v71, v4
	v_add_f32_e32 v9, v10, v9
	v_exp_f32_e32 v14, v14
	v_sub_f32_e32 v15, v72, v4
	v_sub_f32_e32 v50, v50, v4
	v_add_f32_e32 v9, v11, v9
	v_exp_f32_e32 v15, v15
	v_sub_f32_e32 v16, v73, v4
	v_exp_f32_e32 v101, v50
	v_sub_f32_e32 v50, v51, v4
	v_add_f32_e32 v9, v12, v9
	v_exp_f32_e32 v16, v16
	v_sub_f32_e32 v17, v74, v4
	v_exp_f32_e32 v102, v50
	v_sub_f32_e32 v50, v52, v4
	v_add_f32_e32 v9, v13, v9
	v_exp_f32_e32 v17, v17
	v_sub_f32_e32 v66, v75, v4
	v_exp_f32_e32 v103, v50
	v_sub_f32_e32 v50, v53, v4
	v_add_f32_e32 v9, v14, v9
	v_exp_f32_e32 v94, v66
	v_sub_f32_e32 v66, v76, v4
	v_exp_f32_e32 v104, v50
	v_sub_f32_e32 v50, v54, v4
	v_add_f32_e32 v9, v15, v9
	v_exp_f32_e32 v95, v66
	v_sub_f32_e32 v66, v77, v4
	v_exp_f32_e32 v105, v50
	v_sub_f32_e32 v50, v55, v4
	v_add_f32_e32 v9, v16, v9
	v_exp_f32_e32 v96, v66
	v_sub_f32_e32 v66, v78, v4
	v_exp_f32_e32 v106, v50
	v_sub_f32_e32 v50, v56, v4
	v_add_f32_e32 v9, v17, v9
	v_exp_f32_e32 v97, v66
	v_sub_f32_e32 v66, v79, v4
	v_exp_f32_e32 v107, v50
	v_sub_f32_e32 v50, v57, v4
	v_add_f32_e32 v9, v94, v9
	v_exp_f32_e32 v98, v66
	v_sub_f32_e32 v66, v80, v4
	v_exp_f32_e32 v108, v50
	v_sub_f32_e32 v50, v58, v4
	v_add_f32_e32 v9, v95, v9
	v_exp_f32_e32 v99, v66
	v_sub_f32_e32 v66, v81, v4
	v_exp_f32_e32 v109, v50
	v_sub_f32_e32 v50, v59, v4
	v_add_f32_e32 v9, v96, v9
	v_exp_f32_e32 v100, v66
	v_exp_f32_e32 v110, v50
	v_sub_f32_e32 v50, v60, v4
	v_add_f32_e32 v9, v97, v9
	v_exp_f32_e32 v111, v50
	v_sub_f32_e32 v50, v61, v4
	v_add_f32_e32 v9, v98, v9
	v_exp_f32_e32 v112, v50
	v_sub_f32_e32 v50, v62, v4
	v_add_f32_e32 v9, v99, v9
	v_exp_f32_e32 v113, v50
	v_sub_f32_e32 v50, v63, v4
	v_sub_f32_e32 v7, v175, v4
	v_add_f32_e32 v9, v100, v9
	v_exp_f32_e32 v114, v50
	v_sub_f32_e32 v50, v64, v4
	v_sub_f32_e32 v4, v65, v4
	v_exp_f32_e32 v116, v4
	v_exp_f32_e32 v4, v7
	v_add_f32_e32 v7, v101, v9
	v_cvt_pk_bf16_f32 v8, v8, v10
	v_cvt_pk_bf16_f32 v9, v11, v12
	v_cvt_pk_bf16_f32 v10, v13, v14
	v_cvt_pk_bf16_f32 v11, v15, v16
	v_add_u32_e32 v16, v169, v172
	v_add_u32_e32 v117, 0x8800, v16
	ds_read2_b64 v[180:183], v117 offset0:64 offset1:66
	v_pk_mul_f32 v[80:81], v[48:49], v[4:5] op_sel_hi:[1,0]
	v_pk_mul_f32 v[78:79], v[46:47], v[4:5] op_sel_hi:[1,0]
	v_pk_mul_f32 v[76:77], v[44:45], v[4:5] op_sel_hi:[1,0]
	v_pk_mul_f32 v[74:75], v[42:43], v[4:5] op_sel_hi:[1,0]
	v_pk_mul_f32 v[72:73], v[40:41], v[4:5] op_sel_hi:[1,0]
	v_pk_mul_f32 v[70:71], v[38:39], v[4:5] op_sel_hi:[1,0]
	v_pk_mul_f32 v[68:69], v[36:37], v[4:5] op_sel_hi:[1,0]
	v_pk_mul_f32 v[66:67], v[34:35], v[4:5] op_sel_hi:[1,0]
	v_add_u32_e32 v16, 0x9800, v16
	ds_read2_b64 v[188:191], v16 offset0:96 offset1:98
	ds_read2_b64 v[196:199], v117 offset0:68 offset1:70
	ds_read2_b64 v[204:207], v16 offset0:100 offset1:102
	v_exp_f32_e32 v115, v50
	s_waitcnt lgkmcnt(3)
	v_mfma_f32_32x32x16_bf16 v[66:81], v[180:183], v[8:11], v[66:81]
	ds_read2_b64 v[212:215], v117 offset0:72 offset1:74
	v_mul_f32_e64 v64, v32, v4
	v_mul_f32_e64 v65, v33, v4
	v_mul_f32_e64 v62, v30, v4
	v_mul_f32_e64 v63, v31, v4
	v_pk_mul_f32 v[60:61], v[28:29], v[4:5] op_sel_hi:[1,0]
	v_pk_mul_f32 v[58:59], v[26:27], v[4:5] op_sel_hi:[1,0]
	v_pk_mul_f32 v[56:57], v[24:25], v[4:5] op_sel_hi:[1,0]
	v_pk_mul_f32 v[54:55], v[22:23], v[4:5] op_sel_hi:[1,0]
	v_pk_mul_f32 v[52:53], v[20:21], v[4:5] op_sel_hi:[1,0]
	v_pk_mul_f32 v[50:51], v[18:19], v[4:5] op_sel_hi:[1,0]
	v_add_f32_e32 v7, v102, v7
	v_add_f32_e32 v7, v103, v7
	s_waitcnt lgkmcnt(3)
	v_mfma_f32_32x32x16_bf16 v[50:65], v[188:191], v[8:11], v[50:65]
	ds_read2_b64 v[180:183], v16 offset0:104 offset1:106
	v_cvt_pk_bf16_f32 v8, v17, v94
	v_cvt_pk_bf16_f32 v9, v95, v96
	v_cvt_pk_bf16_f32 v10, v97, v98
	v_cvt_pk_bf16_f32 v11, v99, v100
	v_add_f32_e32 v7, v104, v7
	v_add_f32_e32 v7, v105, v7
	s_waitcnt lgkmcnt(3)
	v_mfma_f32_32x32x16_bf16 v[66:81], v[196:199], v[8:11], v[66:81]
	ds_read2_b64 v[188:191], v117 offset0:76 offset1:78
	v_add_f32_e32 v7, v106, v7
	v_add_f32_e32 v7, v107, v7
	v_add_f32_e32 v7, v108, v7
	v_add_f32_e32 v7, v109, v7
	v_add_f32_e32 v7, v110, v7
	v_add_f32_e32 v7, v111, v7
	s_waitcnt lgkmcnt(3)
	v_mfma_f32_32x32x16_bf16 v[50:65], v[204:207], v[8:11], v[50:65]
	ds_read2_b64 v[196:199], v16 offset0:108 offset1:110
	v_cvt_pk_bf16_f32 v8, v101, v102
	v_cvt_pk_bf16_f32 v9, v103, v104
	v_cvt_pk_bf16_f32 v10, v105, v106
	v_cvt_pk_bf16_f32 v11, v107, v108
	v_add_f32_e32 v7, v112, v7
	v_add_f32_e32 v7, v113, v7
	s_waitcnt lgkmcnt(3)
	v_mfma_f32_32x32x16_bf16 v[66:81], v[212:215], v[8:11], v[66:81]
	v_add_f32_e32 v7, v114, v7
	v_add_f32_e32 v7, v115, v7
	v_add_f32_e32 v7, v116, v7
	v_fmac_f32_e32 v7, v157, v4
	s_waitcnt lgkmcnt(2)
	v_mfma_f32_32x32x16_bf16 v[50:65], v[180:183], v[8:11], v[50:65]
	v_cvt_pk_bf16_f32 v8, v109, v110
	v_cvt_pk_bf16_f32 v9, v111, v112
	v_cvt_pk_bf16_f32 v10, v113, v114
	v_cvt_pk_bf16_f32 v11, v115, v116
	s_waitcnt lgkmcnt(1)
	s_nop 0
	v_mfma_f32_32x32x16_bf16 v[66:81], v[188:191], v[8:11], v[66:81]
	s_waitcnt lgkmcnt(0)
	v_mfma_f32_32x32x16_bf16 v[50:65], v[196:199], v[8:11], v[50:65]
